# v9: + xs0 loads hoisted to iteration top, mod-phase silu loop unrolled
# speedup vs baseline: 1.0051x; 1.0051x over previous
; #define LAS __attribute__((address_space(3)))
; #define ws (KP()->ws)
; DI void mod_phase(const Params& p, LAS unsigned char* lds, int tid, int wave, int lane, int G) {
;     if ((int)blockIdx.x >= 192) return;
;     float* mod = (float*)(p.ws + WS_MOD);
;     LAS float* cact = (LAS float*)lds;
;     LAS float* red = (LAS float*)(lds + 32768);
;     for (int i = tid; i < NB * DM; i += NTHREADS) { const float v = p.c[i]; cact[i] = v / (1.f + __expf(-v)); }
.LBB0_5:
	s_or_b64 exec, exec, s[4:5]
	s_lshr_b32 s33, s44, 6
	s_cmpk_gt_i32 s2, 0xbf
	v_and_b32_e32 v64, 63, v1
	s_cbranch_scc1 .LBB0_12
	s_load_dwordx4 s[4:7], s[0:1], 0x8
	s_load_dwordx2 s[8:9], s[0:1], 0x18
	v_lshlrev_b32_e32 v2, 2, v1
	v_mov_b32_e32 v3, 0
	v_add_u32_e32 v4, 0xfffffe00, v1
	v_add_u32_e32 v5, 0, v2
	s_waitcnt lgkmcnt(0)
	v_lshl_add_u64 v[2:3], s[4:5], 0, v[2:3]
	s_mov_b64 s[4:5], 0
	s_mov_b64 s[10:11], 0x1000
	s_movk_i32 s12, 0x1dff
	global_load_dword v16, v[2:3], off
	global_load_dword v17, v[2:3], off offset:2048
	v_lshl_add_u64 v[2:3], v[2:3], 0, s[10:11]
	global_load_dword v18, v[2:3], off
	global_load_dword v19, v[2:3], off offset:2048
	v_lshl_add_u64 v[2:3], v[2:3], 0, s[10:11]
	global_load_dword v20, v[2:3], off
	global_load_dword v21, v[2:3], off offset:2048
	v_lshl_add_u64 v[2:3], v[2:3], 0, s[10:11]
	global_load_dword v22, v[2:3], off
	global_load_dword v23, v[2:3], off offset:2048
	v_lshl_add_u64 v[2:3], v[2:3], 0, s[10:11]
	global_load_dword v24, v[2:3], off
	global_load_dword v25, v[2:3], off offset:2048
	v_lshl_add_u64 v[2:3], v[2:3], 0, s[10:11]
	global_load_dword v26, v[2:3], off
	global_load_dword v27, v[2:3], off offset:2048
	v_lshl_add_u64 v[2:3], v[2:3], 0, s[10:11]
	global_load_dword v28, v[2:3], off
	global_load_dword v29, v[2:3], off offset:2048
	v_lshl_add_u64 v[2:3], v[2:3], 0, s[10:11]
	global_load_dword v30, v[2:3], off
	global_load_dword v31, v[2:3], off offset:2048
	s_waitcnt vmcnt(15)
	v_mul_f32_e32 v7, 0xbfb8aa3b, v16
	v_exp_f32_e32 v7, v7
	s_nop 0
	v_add_f32_e32 v7, 1.0, v7
	v_div_scale_f32 v8, s[14:15], v7, v7, v16
	v_rcp_f32_e32 v9, v8
	v_div_scale_f32 v10, vcc, v16, v7, v16
	v_fma_f32 v11, -v8, v9, 1.0
	v_fmac_f32_e32 v9, v11, v9
	v_mul_f32_e32 v11, v10, v9
	v_fma_f32 v12, -v8, v11, v10
	v_fmac_f32_e32 v11, v12, v9
	v_fma_f32 v8, -v8, v11, v10
	v_div_fmas_f32 v8, v8, v9, v11
	v_div_fixup_f32 v16, v8, v7, v16
	ds_write_b32 v5, v16
	s_waitcnt vmcnt(14)
	v_mul_f32_e32 v7, 0xbfb8aa3b, v17
	v_exp_f32_e32 v7, v7
	s_nop 0
	v_add_f32_e32 v7, 1.0, v7
	v_div_scale_f32 v8, s[14:15], v7, v7, v17
	v_rcp_f32_e32 v9, v8
	v_div_scale_f32 v10, vcc, v17, v7, v17
	v_fma_f32 v11, -v8, v9, 1.0
	v_fmac_f32_e32 v9, v11, v9
	v_mul_f32_e32 v11, v10, v9
	v_fma_f32 v12, -v8, v11, v10
	v_fmac_f32_e32 v11, v12, v9
	v_fma_f32 v8, -v8, v11, v10
	v_div_fmas_f32 v8, v8, v9, v11
	v_div_fixup_f32 v17, v8, v7, v17
	ds_write_b32 v5, v17 offset:2048
	s_waitcnt vmcnt(13)
	v_mul_f32_e32 v7, 0xbfb8aa3b, v18
	v_exp_f32_e32 v7, v7
	s_nop 0
	v_add_f32_e32 v7, 1.0, v7
	v_div_scale_f32 v8, s[14:15], v7, v7, v18
	v_rcp_f32_e32 v9, v8
	v_div_scale_f32 v10, vcc, v18, v7, v18
	v_fma_f32 v11, -v8, v9, 1.0
	v_fmac_f32_e32 v9, v11, v9
	v_mul_f32_e32 v11, v10, v9
	v_fma_f32 v12, -v8, v11, v10
	v_fmac_f32_e32 v11, v12, v9
	v_fma_f32 v8, -v8, v11, v10
	v_div_fmas_f32 v8, v8, v9, v11
	v_div_fixup_f32 v18, v8, v7, v18
	ds_write_b32 v5, v18 offset:4096
	s_waitcnt vmcnt(12)
	v_mul_f32_e32 v7, 0xbfb8aa3b, v19
	v_exp_f32_e32 v7, v7
	s_nop 0
	v_add_f32_e32 v7, 1.0, v7
	v_div_scale_f32 v8, s[14:15], v7, v7, v19
	v_rcp_f32_e32 v9, v8
	v_div_scale_f32 v10, vcc, v19, v7, v19
	v_fma_f32 v11, -v8, v9, 1.0
	v_fmac_f32_e32 v9, v11, v9
	v_mul_f32_e32 v11, v10, v9
	v_fma_f32 v12, -v8, v11, v10
	v_fmac_f32_e32 v11, v12, v9
	v_fma_f32 v8, -v8, v11, v10
	v_div_fmas_f32 v8, v8, v9, v11
	v_div_fixup_f32 v19, v8, v7, v19
	ds_write_b32 v5, v19 offset:6144
	s_waitcnt vmcnt(11)
	v_mul_f32_e32 v7, 0xbfb8aa3b, v20
	v_exp_f32_e32 v7, v7
	s_nop 0
	v_add_f32_e32 v7, 1.0, v7
	v_div_scale_f32 v8, s[14:15], v7, v7, v20
	v_rcp_f32_e32 v9, v8
	v_div_scale_f32 v10, vcc, v20, v7, v20
	v_fma_f32 v11, -v8, v9, 1.0
	v_fmac_f32_e32 v9, v11, v9
	v_mul_f32_e32 v11, v10, v9
	v_fma_f32 v12, -v8, v11, v10
	v_fmac_f32_e32 v11, v12, v9
	v_fma_f32 v8, -v8, v11, v10
	v_div_fmas_f32 v8, v8, v9, v11
	v_div_fixup_f32 v20, v8, v7, v20
	ds_write_b32 v5, v20 offset:8192
	s_waitcnt vmcnt(10)
	v_mul_f32_e32 v7, 0xbfb8aa3b, v21
	v_exp_f32_e32 v7, v7
	s_nop 0
	v_add_f32_e32 v7, 1.0, v7
	v_div_scale_f32 v8, s[14:15], v7, v7, v21
	v_rcp_f32_e32 v9, v8
	v_div_scale_f32 v10, vcc, v21, v7, v21
	v_fma_f32 v11, -v8, v9, 1.0
	v_fmac_f32_e32 v9, v11, v9
	v_mul_f32_e32 v11, v10, v9
	v_fma_f32 v12, -v8, v11, v10
	v_fmac_f32_e32 v11, v12, v9
	v_fma_f32 v8, -v8, v11, v10
	v_div_fmas_f32 v8, v8, v9, v11
	v_div_fixup_f32 v21, v8, v7, v21
	ds_write_b32 v5, v21 offset:10240
	s_waitcnt vmcnt(9)
	v_mul_f32_e32 v7, 0xbfb8aa3b, v22
	v_exp_f32_e32 v7, v7
	s_nop 0
	v_add_f32_e32 v7, 1.0, v7
	v_div_scale_f32 v8, s[14:15], v7, v7, v22
	v_rcp_f32_e32 v9, v8
	v_div_scale_f32 v10, vcc, v22, v7, v22
	v_fma_f32 v11, -v8, v9, 1.0
	v_fmac_f32_e32 v9, v11, v9
	v_mul_f32_e32 v11, v10, v9
	v_fma_f32 v12, -v8, v11, v10
	v_fmac_f32_e32 v11, v12, v9
	v_fma_f32 v8, -v8, v11, v10
	v_div_fmas_f32 v8, v8, v9, v11
	v_div_fixup_f32 v22, v8, v7, v22
	ds_write_b32 v5, v22 offset:12288
	s_waitcnt vmcnt(8)
; DI void mod_phase(const Params& p, LAS unsigned char* lds, int tid, int wave, int lane, int G) {
;     ...
;     for (int i = tid; i < NB * DM; i += NTHREADS) { const float v = p.c[i]; cact[i] = v / (1.f + __expf(-v)); }
;     __syncthreads();
;     for (int item = blockIdx.x; item < 192; item += G) {
;         const int l = item / 48, n0 = (item % 48) * 128;
;         const float* wp = p.ada_w + ((size_t)l * DM + wave * 128) * 6144 + n0 + 2 * lane;
	v_mul_f32_e32 v7, 0xbfb8aa3b, v23
	v_exp_f32_e32 v7, v7
	s_nop 0
	v_add_f32_e32 v7, 1.0, v7
	v_div_scale_f32 v8, s[14:15], v7, v7, v23
	v_rcp_f32_e32 v9, v8
	v_div_scale_f32 v10, vcc, v23, v7, v23
	v_fma_f32 v11, -v8, v9, 1.0
	v_fmac_f32_e32 v9, v11, v9
	v_mul_f32_e32 v11, v10, v9
	v_fma_f32 v12, -v8, v11, v10
	v_fmac_f32_e32 v11, v12, v9
	v_fma_f32 v8, -v8, v11, v10
	v_div_fmas_f32 v8, v8, v9, v11
	v_div_fixup_f32 v23, v8, v7, v23
	ds_write_b32 v5, v23 offset:14336
	s_waitcnt vmcnt(7)
	v_mul_f32_e32 v7, 0xbfb8aa3b, v24
	v_exp_f32_e32 v7, v7
	s_nop 0
	v_add_f32_e32 v7, 1.0, v7
	v_div_scale_f32 v8, s[14:15], v7, v7, v24
	v_rcp_f32_e32 v9, v8
	v_div_scale_f32 v10, vcc, v24, v7, v24
	v_fma_f32 v11, -v8, v9, 1.0
	v_fmac_f32_e32 v9, v11, v9
	v_mul_f32_e32 v11, v10, v9
	v_fma_f32 v12, -v8, v11, v10
	v_fmac_f32_e32 v11, v12, v9
	v_fma_f32 v8, -v8, v11, v10
	v_div_fmas_f32 v8, v8, v9, v11
	v_div_fixup_f32 v24, v8, v7, v24
	ds_write_b32 v5, v24 offset:16384
	s_waitcnt vmcnt(6)
	v_mul_f32_e32 v7, 0xbfb8aa3b, v25
	v_exp_f32_e32 v7, v7
	s_nop 0
	v_add_f32_e32 v7, 1.0, v7
	v_div_scale_f32 v8, s[14:15], v7, v7, v25
	v_rcp_f32_e32 v9, v8
	v_div_scale_f32 v10, vcc, v25, v7, v25
	v_fma_f32 v11, -v8, v9, 1.0
	v_fmac_f32_e32 v9, v11, v9
	v_mul_f32_e32 v11, v10, v9
	v_fma_f32 v12, -v8, v11, v10
	v_fmac_f32_e32 v11, v12, v9
	v_fma_f32 v8, -v8, v11, v10
	v_div_fmas_f32 v8, v8, v9, v11
	v_div_fixup_f32 v25, v8, v7, v25
	ds_write_b32 v5, v25 offset:18432
	s_waitcnt vmcnt(5)
	v_mul_f32_e32 v7, 0xbfb8aa3b, v26
	v_exp_f32_e32 v7, v7
	s_nop 0
	v_add_f32_e32 v7, 1.0, v7
	v_div_scale_f32 v8, s[14:15], v7, v7, v26
	v_rcp_f32_e32 v9, v8
	v_div_scale_f32 v10, vcc, v26, v7, v26
	v_fma_f32 v11, -v8, v9, 1.0
	v_fmac_f32_e32 v9, v11, v9
	v_mul_f32_e32 v11, v10, v9
	v_fma_f32 v12, -v8, v11, v10
	v_fmac_f32_e32 v11, v12, v9
	v_fma_f32 v8, -v8, v11, v10
	v_div_fmas_f32 v8, v8, v9, v11
	v_div_fixup_f32 v26, v8, v7, v26
	ds_write_b32 v5, v26 offset:20480
	s_waitcnt vmcnt(4)
	v_mul_f32_e32 v7, 0xbfb8aa3b, v27
	v_exp_f32_e32 v7, v7
	s_nop 0
	v_add_f32_e32 v7, 1.0, v7
	v_div_scale_f32 v8, s[14:15], v7, v7, v27
	v_rcp_f32_e32 v9, v8
	v_div_scale_f32 v10, vcc, v27, v7, v27
	v_fma_f32 v11, -v8, v9, 1.0
	v_fmac_f32_e32 v9, v11, v9
	v_mul_f32_e32 v11, v10, v9
	v_fma_f32 v12, -v8, v11, v10
	v_fmac_f32_e32 v11, v12, v9
	v_fma_f32 v8, -v8, v11, v10
	v_div_fmas_f32 v8, v8, v9, v11
	v_div_fixup_f32 v27, v8, v7, v27
	ds_write_b32 v5, v27 offset:22528
	s_waitcnt vmcnt(3)
	v_mul_f32_e32 v7, 0xbfb8aa3b, v28
	v_exp_f32_e32 v7, v7
	s_nop 0
	v_add_f32_e32 v7, 1.0, v7
	v_div_scale_f32 v8, s[14:15], v7, v7, v28
	v_rcp_f32_e32 v9, v8
	v_div_scale_f32 v10, vcc, v28, v7, v28
	v_fma_f32 v11, -v8, v9, 1.0
	v_fmac_f32_e32 v9, v11, v9
	v_mul_f32_e32 v11, v10, v9
	v_fma_f32 v12, -v8, v11, v10
	v_fmac_f32_e32 v11, v12, v9
	v_fma_f32 v8, -v8, v11, v10
	v_div_fmas_f32 v8, v8, v9, v11
	v_div_fixup_f32 v28, v8, v7, v28
	ds_write_b32 v5, v28 offset:24576
	s_waitcnt vmcnt(2)
	v_mul_f32_e32 v7, 0xbfb8aa3b, v29
	v_exp_f32_e32 v7, v7
	s_nop 0
	v_add_f32_e32 v7, 1.0, v7
	v_div_scale_f32 v8, s[14:15], v7, v7, v29
	v_rcp_f32_e32 v9, v8
	v_div_scale_f32 v10, vcc, v29, v7, v29
	v_fma_f32 v11, -v8, v9, 1.0
	v_fmac_f32_e32 v9, v11, v9
	v_mul_f32_e32 v11, v10, v9
	v_fma_f32 v12, -v8, v11, v10
	v_fmac_f32_e32 v11, v12, v9
	v_fma_f32 v8, -v8, v11, v10
	v_div_fmas_f32 v8, v8, v9, v11
	v_div_fixup_f32 v29, v8, v7, v29
	ds_write_b32 v5, v29 offset:26624
	s_waitcnt vmcnt(1)
	v_mul_f32_e32 v7, 0xbfb8aa3b, v30
	v_exp_f32_e32 v7, v7
	s_nop 0
	v_add_f32_e32 v7, 1.0, v7
	v_div_scale_f32 v8, s[14:15], v7, v7, v30
	v_rcp_f32_e32 v9, v8
	v_div_scale_f32 v10, vcc, v30, v7, v30
	v_fma_f32 v11, -v8, v9, 1.0
	v_fmac_f32_e32 v9, v11, v9
	v_mul_f32_e32 v11, v10, v9
	v_fma_f32 v12, -v8, v11, v10
	v_fmac_f32_e32 v11, v12, v9
	v_fma_f32 v8, -v8, v11, v10
	v_div_fmas_f32 v8, v8, v9, v11
	v_div_fixup_f32 v30, v8, v7, v30
	ds_write_b32 v5, v30 offset:28672
	s_waitcnt vmcnt(0)
	v_mul_f32_e32 v7, 0xbfb8aa3b, v31
	v_exp_f32_e32 v7, v7
	s_nop 0
	v_add_f32_e32 v7, 1.0, v7
	v_div_scale_f32 v8, s[14:15], v7, v7, v31
	v_rcp_f32_e32 v9, v8
	v_div_scale_f32 v10, vcc, v31, v7, v31
	v_fma_f32 v11, -v8, v9, 1.0
	v_fmac_f32_e32 v9, v11, v9
	v_mul_f32_e32 v11, v10, v9
	v_fma_f32 v12, -v8, v11, v10
	v_fmac_f32_e32 v11, v12, v9
	v_fma_f32 v8, -v8, v11, v10
	v_div_fmas_f32 v8, v8, v9, v11
	v_div_fixup_f32 v31, v8, v7, v31
	ds_write_b32 v5, v31 offset:30720
	s_or_b64 exec, exec, s[4:5]
	v_and_b32_e32 v66, 0x7f, v1
	v_lshlrev_b32_e32 v34, 2, v66
	s_lshl_b32 s4, s33, 9
	v_add_u32_e32 v3, 0, v34
	v_and_b32_e32 v4, 0x380, v1
	s_add_i32 s17, s4, 0
	s_lshl_b32 s4, s33, 12
	v_lshl_add_u32 v67, v4, 2, v3
	v_add_u32_e32 v4, 0x200, v1
	v_lshlrev_b32_e32 v2, 1, v64
	v_mov_b32_e32 v35, 0
	s_add_i32 s4, s4, 0
	v_and_b32_e32 v5, 0x780, v4
	s_lshl_b32 s16, s33, 7
	s_mov_b32 s5, 0
	v_lshl_add_u32 v65, v64, 3, s4
	v_lshl_add_u64 v[36:37], s[40:41], 0, v[34:35]
	v_lshrrev_b32_e32 v68, 7, v1
	v_lshl_add_u32 v69, v5, 2, v3
	v_lshrrev_b32_e32 v70, 7, v4
	s_movk_i32 s18, 0x6000
	v_lshlrev_b32_e32 v34, 2, v2
	s_mov_b32 s19, 0xc000
	s_mov_b32 s22, 0x12000
	s_mov_b32 s23, 0x18000
	s_mov_b32 s24, s2
	s_waitcnt lgkmcnt(0)
	s_barrier

; DI unsigned cvtpk(float lo, float hi) { f32x2_t v = {lo, hi}; bf16x2_t b = __builtin_convertvector(v, bf16x2_t); return __builtin_bit_cast(unsigned, b); }
; DI void xs0_phase(const float* xs, const float* gain, const float* mod_l, bf16* h, unsigned long long* rowsq, int NGW, const int wave_s) {
;     ...
;         for (int r = 0; r < 4; ++r) { const int m = m0 + r * NGW; if (m >= MTOK) break;
;             const int b = m >> 12; float ss = 0.f;
; #pragma unroll
;             for (int j = 0; j < 4; ++j) ss += (v[r][j].x * v[r][j].x + v[r][j].y * v[r][j].y) + (v[r][j].z * v[r][j].z + v[r][j].w * v[r][j].w);
;             ss = wave_sum(ss, x32);
;             if (lane == 0) rowsq[m] = (unsigned long long)(ss * 4294967296.f);
;             unsigned long long* o8 = (unsigned long long*)(h + (size_t)m * DM) + lane;
; #pragma unroll
;             for (int j = 0; j < 4; ++j) { const int col = 4 * lane + 256 * j;
;                 const f32x4 g = *(const f32x4*)(gain + col), sc = *(const f32x4*)(mod_l + (size_t)b * 6144 + DM + col);
;                 const f32x4 y = v[r][j] * (g * (sc + 1.f));
;                 o8[64 * j] = (unsigned long long)cvtpk(y.x, y.y) | ((unsigned long long)cvtpk(y.z, y.w) << 32); } }
.LBB0_109:
	s_or_b64 exec, exec, s[36:37]
	s_ashr_i32 s36, s34, 12
	s_lshl_b64 s[34:35], s[34:35], 11
	s_mul_hi_i32 s37, s36, 0x6000
	s_mulk_i32 s36, 0x6000
	s_add_u32 s36, s8, s36
	s_addc_u32 s37, s9, s37
	v_lshl_add_u64 v[24:25], v[64:65], 2, s[36:37]
	v_add_co_u32_e32 v26, vcc, s7, v24
	s_nop 1
	v_addc_co_u32_e32 v27, vcc, 0, v25, vcc
	s_waitcnt lgkmcnt(0)
	v_mov_b32_e32 v16, v164
	v_mov_b32_e32 v17, v165
	v_mov_b32_e32 v18, v166
	v_mov_b32_e32 v19, v167
	v_mov_b32_e32 v20, v100
	v_mov_b32_e32 v21, v101
	v_mov_b32_e32 v22, v102
	v_mov_b32_e32 v23, v103
	v_lshl_add_u64 v[26:27], v[70:71], 0, s[34:35]
	v_lshl_add_u64 v[24:25], v[24:25], 0, s[28:29]
	v_pk_add_f32 v[18:19], v[18:19], 1.0 op_sel_hi:[1,0]
	v_pk_add_f32 v[16:17], v[16:17], 1.0 op_sel_hi:[1,0]
	v_pk_mul_f32 v[18:19], v[22:23], v[18:19]
	v_pk_mul_f32 v[16:17], v[20:21], v[16:17]
	v_pk_mul_f32 v[14:15], v[14:15], v[18:19]
	v_pk_mul_f32 v[12:13], v[12:13], v[16:17]
	s_nop 0
	v_cvt_pk_bf16_f32 v12, v12, v13
	v_cvt_pk_bf16_f32 v13, v14, v15
	global_store_dwordx2 v[26:27], v[12:13], off
	v_mov_b32_e32 v12, v168
	v_mov_b32_e32 v13, v169
	v_mov_b32_e32 v14, v170
	v_mov_b32_e32 v15, v171
	s_nop 0
	v_mov_b32_e32 v16, v104
	v_mov_b32_e32 v17, v105
	v_mov_b32_e32 v18, v106
	v_mov_b32_e32 v19, v107
	v_pk_add_f32 v[14:15], v[14:15], 1.0 op_sel_hi:[1,0]
	v_pk_add_f32 v[12:13], v[12:13], 1.0 op_sel_hi:[1,0]
	v_pk_mul_f32 v[14:15], v[18:19], v[14:15]
	v_pk_mul_f32 v[12:13], v[16:17], v[12:13]
	v_pk_mul_f32 v[10:11], v[10:11], v[14:15]
	v_pk_mul_f32 v[8:9], v[8:9], v[12:13]
	s_nop 0
	v_cvt_pk_bf16_f32 v8, v8, v9
	v_cvt_pk_bf16_f32 v9, v10, v11
	global_store_dwordx2 v[26:27], v[8:9], off offset:512
	v_mov_b32_e32 v8, v172
	v_mov_b32_e32 v9, v173
	v_mov_b32_e32 v10, v174
	v_mov_b32_e32 v11, v175
	s_nop 0
	v_mov_b32_e32 v12, v108
	v_mov_b32_e32 v13, v109
	v_mov_b32_e32 v14, v110
	v_mov_b32_e32 v15, v111
	v_pk_add_f32 v[10:11], v[10:11], 1.0 op_sel_hi:[1,0]
	v_pk_add_f32 v[8:9], v[8:9], 1.0 op_sel_hi:[1,0]
	v_pk_mul_f32 v[10:11], v[14:15], v[10:11]
	v_pk_mul_f32 v[8:9], v[12:13], v[8:9]
	v_pk_mul_f32 v[6:7], v[6:7], v[10:11]
	v_pk_mul_f32 v[4:5], v[4:5], v[8:9]
	s_nop 0
	v_cvt_pk_bf16_f32 v4, v4, v5
	v_cvt_pk_bf16_f32 v5, v6, v7
	global_store_dwordx2 v[26:27], v[4:5], off offset:1024
	v_mov_b32_e32 v4, v176
	v_mov_b32_e32 v5, v177
	v_mov_b32_e32 v6, v178
	v_mov_b32_e32 v7, v179
	s_nop 0
	v_mov_b32_e32 v8, v112
	v_mov_b32_e32 v9, v113
	v_mov_b32_e32 v10, v114
	v_mov_b32_e32 v11, v115
	v_pk_add_f32 v[6:7], v[6:7], 1.0 op_sel_hi:[1,0]
	v_pk_add_f32 v[4:5], v[4:5], 1.0 op_sel_hi:[1,0]
	v_pk_mul_f32 v[6:7], v[10:11], v[6:7]
	v_pk_mul_f32 v[4:5], v[8:9], v[4:5]
	v_pk_mul_f32 v[2:3], v[2:3], v[6:7]
	v_pk_mul_f32 v[0:1], v[0:1], v[4:5]
	s_nop 0
	v_cvt_pk_bf16_f32 v0, v0, v1
	v_cvt_pk_bf16_f32 v1, v2, v3
	global_store_dwordx2 v[26:27], v[0:1], off offset:1536

; DI void xs0_phase(const float* xs, const float* gain, const float* mod_l, bf16* h, unsigned long long* rowsq, int NGW, const int wave_s) {
;     ...
;     for (int m0 = gw; m0 < MTOK; m0 += 4 * NGW) {
;         f32x4 v[4][4];
; #pragma unroll
;         for (int r = 0; r < 4; ++r) { const int m = m0 + r * NGW; const f32x4* xr = (const f32x4*)(xs + (size_t)((m < MTOK) ? m : m0) * DM) + lane;
; #pragma unroll
;             for (int j = 0; j < 4; ++j) v[r][j] = __builtin_nontemporal_load(xr + 64 * j); }
; #pragma unroll
;         for (int r = 0; r < 4; ++r) { const int m = m0 + r * NGW; if (m >= MTOK) break;
;             const int b = m >> 12; float ss = 0.f;
; #pragma unroll
;             for (int j = 0; j < 4; ++j) ss += (v[r][j].x * v[r][j].x + v[r][j].y * v[r][j].y) + (v[r][j].z * v[r][j].z + v[r][j].w * v[r][j].w);
;             ss = wave_sum(ss, x32);
;             if (lane == 0) rowsq[m] = (unsigned long long)(ss * 4294967296.f);
.LBB0_111:
	global_load_dwordx4 v[60:63], v[74:75], off nt
	global_load_dwordx4 v[56:59], v[74:75], off offset:1024 nt
	global_load_dwordx4 v[52:55], v[74:75], off offset:2048 nt
	global_load_dwordx4 v[48:51], v[74:75], off offset:3072 nt
	s_add_i32 s35, s95, s6
	s_cmp_lt_i32 s35, 0x8000
	s_cselect_b64 s[46:47], -1, 0
	s_and_b64 s[36:37], s[46:47], exec
	s_cselect_b32 s36, s35, s6
	s_ashr_i32 s37, s36, 31
	s_add_i32 s38, s45, s6
	s_lshl_b64 s[36:37], s[36:37], 12
	s_cmp_lt_i32 s38, 0x8000
	s_cselect_b64 s[40:41], -1, 0
	v_lshl_add_u64 v[0:1], v[66:67], 0, s[36:37]
	s_and_b64 s[36:37], s[40:41], exec
	s_cselect_b32 s36, s38, s6
	s_ashr_i32 s37, s36, 31
	s_add_i32 s34, s50, s6
	s_lshl_b64 s[36:37], s[36:37], 12
	s_cmp_lt_i32 s34, 0x8000
	global_load_dwordx4 v[44:47], v[0:1], off nt
	global_load_dwordx4 v[40:43], v[0:1], off offset:1024 nt
	global_load_dwordx4 v[36:39], v[0:1], off offset:2048 nt
	global_load_dwordx4 v[32:35], v[0:1], off offset:3072 nt
	v_lshl_add_u64 v[0:1], v[66:67], 0, s[36:37]
	s_cselect_b64 s[36:37], -1, 0
	s_and_b64 s[48:49], s[36:37], exec
	s_cselect_b32 s48, s34, s6
	s_ashr_i32 s49, s48, 31
	s_lshl_b64 s[48:49], s[48:49], 12
	global_load_dwordx4 v[28:31], v[0:1], off nt
	global_load_dwordx4 v[24:27], v[0:1], off offset:1024 nt
	global_load_dwordx4 v[20:23], v[0:1], off offset:2048 nt
	global_load_dwordx4 v[16:19], v[0:1], off offset:3072 nt
	v_lshl_add_u64 v[0:1], v[66:67], 0, s[48:49]
	global_load_dwordx4 v[12:15], v[0:1], off nt
	global_load_dwordx4 v[8:11], v[0:1], off offset:1024 nt
	global_load_dwordx4 v[4:7], v[0:1], off offset:2048 nt
	s_nop 0
	global_load_dwordx4 v[0:3], v[0:1], off offset:3072 nt
	s_ashr_i32 s98, s6, 12
	s_mul_hi_i32 s99, s98, 0x6000
	s_mulk_i32 s98, 0x6000
	s_add_u32 s98, s8, s98
	s_addc_u32 s99, s9, s99
	s_add_u32 s98, s98, 0x1000
	s_addc_u32 s99, s99, 0
	v_lshl_add_u64 v[180:181], v[64:65], 2, s[98:99]
	global_load_dwordx4 v[116:119], v[180:181], off
	global_load_dwordx4 v[120:123], v[180:181], off offset:1024
	global_load_dwordx4 v[124:127], v[180:181], off offset:2048
	global_load_dwordx4 v[128:131], v[180:181], off offset:3072
	s_ashr_i32 s98, s35, 12
	s_mul_hi_i32 s99, s98, 0x6000
	s_mulk_i32 s98, 0x6000
	s_add_u32 s98, s8, s98
	s_addc_u32 s99, s9, s99
	s_add_u32 s98, s98, 0x1000
	s_addc_u32 s99, s99, 0
	v_lshl_add_u64 v[180:181], v[64:65], 2, s[98:99]
	global_load_dwordx4 v[132:135], v[180:181], off
	global_load_dwordx4 v[136:139], v[180:181], off offset:1024
	global_load_dwordx4 v[140:143], v[180:181], off offset:2048
	global_load_dwordx4 v[144:147], v[180:181], off offset:3072
	s_ashr_i32 s98, s38, 12
	s_mul_hi_i32 s99, s98, 0x6000
	s_mulk_i32 s98, 0x6000
	s_add_u32 s98, s8, s98
	s_addc_u32 s99, s9, s99
	s_add_u32 s98, s98, 0x1000
	s_addc_u32 s99, s99, 0
	v_lshl_add_u64 v[180:181], v[64:65], 2, s[98:99]
	global_load_dwordx4 v[148:151], v[180:181], off
	global_load_dwordx4 v[152:155], v[180:181], off offset:1024
	global_load_dwordx4 v[156:159], v[180:181], off offset:2048
	global_load_dwordx4 v[160:163], v[180:181], off offset:3072
	s_ashr_i32 s98, s34, 12
	s_mul_hi_i32 s99, s98, 0x6000
	s_mulk_i32 s98, 0x6000
	s_add_u32 s98, s8, s98
	s_addc_u32 s99, s9, s99
	s_add_u32 s98, s98, 0x1000
	s_addc_u32 s99, s99, 0
	v_lshl_add_u64 v[180:181], v[64:65], 2, s[98:99]
	global_load_dwordx4 v[164:167], v[180:181], off
	global_load_dwordx4 v[168:171], v[180:181], off offset:1024
	global_load_dwordx4 v[172:175], v[180:181], off offset:2048
	global_load_dwordx4 v[176:179], v[180:181], off offset:3072
	s_waitcnt vmcnt(0)
	v_mul_f32_e32 v78, v61, v61
	v_mul_f32_e32 v79, v63, v63
	v_mul_f32_e32 v80, v57, v57
	v_mul_f32_e32 v81, v59, v59
	v_mul_f32_e32 v82, v53, v53
	v_mul_f32_e32 v83, v55, v55
	v_fmac_f32_e32 v78, v60, v60
	v_fmac_f32_e32 v79, v62, v62
	v_fmac_f32_e32 v80, v56, v56
	v_fmac_f32_e32 v81, v58, v58
	v_mul_f32_e32 v84, v49, v49
	v_mul_f32_e32 v85, v51, v51
	v_fmac_f32_e32 v82, v52, v52
	v_fmac_f32_e32 v83, v54, v54
	v_add_f32_e32 v78, v78, v79
	v_add_f32_e32 v79, v80, v81
	v_fmac_f32_e32 v84, v48, v48
	v_fmac_f32_e32 v85, v50, v50
	v_add_f32_e32 v80, v82, v83
	v_add_f32_e32 v78, v78, v79
	v_add_f32_e32 v78, v78, v80
	v_add_f32_e32 v79, v84, v85
	v_add_f32_e32 v78, v78, v79
	ds_swizzle_b32 v79, v78 offset:swizzle(SWAP,1)
	s_waitcnt lgkmcnt(0)
	v_add_f32_e32 v78, v78, v79
	ds_swizzle_b32 v79, v78 offset:swizzle(SWAP,2)
	s_waitcnt lgkmcnt(0)
	v_add_f32_e32 v78, v78, v79
	ds_swizzle_b32 v79, v78 offset:swizzle(SWAP,4)
	s_waitcnt lgkmcnt(0)
	v_add_f32_e32 v78, v78, v79
	ds_swizzle_b32 v79, v78 offset:swizzle(SWAP,8)
	s_waitcnt lgkmcnt(0)
	v_add_f32_e32 v78, v78, v79
	ds_swizzle_b32 v79, v78 offset:swizzle(SWAP,16)
	s_waitcnt lgkmcnt(0)
	v_add_f32_e32 v78, v78, v79
	ds_bpermute_b32 v79, v76, v78
	s_and_saveexec_b64 s[48:49], s[4:5]
	s_cbranch_execz .LBB0_113
	s_waitcnt lgkmcnt(0)
	v_add_f32_e32 v78, v78, v79
	v_mul_f32_e32 v78, 0x4f800000, v78
	v_trunc_f32_e32 v78, v78
	v_mul_f32_e32 v79, 0x2f800000, v78
	v_floor_f32_e32 v79, v79
	v_fmac_f32_e32 v78, 0xcf800000, v79
	v_cvt_u32_f32_e32 v78, v78
	v_cvt_u32_f32_e32 v79, v79
	s_add_u32 s52, s30, s22
	s_addc_u32 s53, s31, s23
	global_store_dwordx2 v77, v[78:79], s[52:53]
; DI unsigned cvtpk(float lo, float hi) { f32x2_t v = {lo, hi}; bf16x2_t b = __builtin_convertvector(v, bf16x2_t); return __builtin_bit_cast(unsigned, b); }
; DI void xs0_phase(const float* xs, const float* gain, const float* mod_l, bf16* h, unsigned long long* rowsq, int NGW, const int wave_s) {
;     ...
;         for (int r = 0; r < 4; ++r) { const int m = m0 + r * NGW; if (m >= MTOK) break;
;             const int b = m >> 12; float ss = 0.f;
; #pragma unroll
;             for (int j = 0; j < 4; ++j) ss += (v[r][j].x * v[r][j].x + v[r][j].y * v[r][j].y) + (v[r][j].z * v[r][j].z + v[r][j].w * v[r][j].w);
;             ss = wave_sum(ss, x32);
;             if (lane == 0) rowsq[m] = (unsigned long long)(ss * 4294967296.f);
;             unsigned long long* o8 = (unsigned long long*)(h + (size_t)m * DM) + lane;
; #pragma unroll
;             for (int j = 0; j < 4; ++j) { const int col = 4 * lane + 256 * j;
;                 const f32x4 g = *(const f32x4*)(gain + col), sc = *(const f32x4*)(mod_l + (size_t)b * 6144 + DM + col);
;                 const f32x4 y = v[r][j] * (g * (sc + 1.f));
;                 o8[64 * j] = (unsigned long long)cvtpk(y.x, y.y) | ((unsigned long long)cvtpk(y.z, y.w) << 32); } }
.LBB0_113:
	s_or_b64 exec, exec, s[48:49]
	s_ashr_i32 s39, s6, 12
	s_mul_hi_i32 s49, s39, 0x6000
	s_mulk_i32 s39, 0x6000
	s_add_u32 s48, s8, s39
	s_addc_u32 s49, s9, s49
	v_lshl_add_u64 v[86:87], v[64:65], 2, s[48:49]
	v_add_co_u32_e32 v78, vcc, s7, v86
	v_lshl_add_u64 v[88:89], s[24:25], 0, v[68:69]
	s_waitcnt lgkmcnt(0)
	v_addc_co_u32_e32 v79, vcc, 0, v87, vcc
	v_mov_b32_e32 v78, v116
	v_mov_b32_e32 v79, v117
	v_mov_b32_e32 v80, v118
	v_mov_b32_e32 v81, v119
	s_nop 0
	v_mov_b32_e32 v82, v100
	v_mov_b32_e32 v83, v101
	v_mov_b32_e32 v84, v102
	v_mov_b32_e32 v85, v103
	v_add_co_u32_e32 v88, vcc, s13, v88
	v_lshl_add_u64 v[86:87], v[86:87], 0, s[28:29]
	s_nop 0
	v_addc_co_u32_e32 v89, vcc, 0, v89, vcc
	s_andn2_b64 vcc, exec, s[46:47]
	v_pk_add_f32 v[80:81], v[80:81], 1.0 op_sel_hi:[1,0]
	v_pk_add_f32 v[78:79], v[78:79], 1.0 op_sel_hi:[1,0]
	v_pk_mul_f32 v[80:81], v[84:85], v[80:81]
	v_pk_mul_f32 v[78:79], v[82:83], v[78:79]
	v_pk_mul_f32 v[62:63], v[62:63], v[80:81]
	v_pk_mul_f32 v[60:61], v[60:61], v[78:79]
	s_nop 0
	v_cvt_pk_bf16_f32 v60, v60, v61
	v_cvt_pk_bf16_f32 v61, v62, v63
	global_store_dwordx2 v[88:89], v[60:61], off
	v_mov_b32_e32 v60, v120
	v_mov_b32_e32 v61, v121
	v_mov_b32_e32 v62, v122
	v_mov_b32_e32 v63, v123
	s_nop 0
	v_mov_b32_e32 v78, v104
	v_mov_b32_e32 v79, v105
	v_mov_b32_e32 v80, v106
	v_mov_b32_e32 v81, v107
	v_pk_add_f32 v[62:63], v[62:63], 1.0 op_sel_hi:[1,0]
	v_pk_add_f32 v[60:61], v[60:61], 1.0 op_sel_hi:[1,0]
	v_pk_mul_f32 v[62:63], v[80:81], v[62:63]
	v_pk_mul_f32 v[60:61], v[78:79], v[60:61]
	v_pk_mul_f32 v[58:59], v[58:59], v[62:63]
	v_pk_mul_f32 v[56:57], v[56:57], v[60:61]
	s_nop 0
	v_cvt_pk_bf16_f32 v56, v56, v57
	v_cvt_pk_bf16_f32 v57, v58, v59
	global_store_dwordx2 v[88:89], v[56:57], off offset:512
	v_mov_b32_e32 v56, v124
	v_mov_b32_e32 v57, v125
	v_mov_b32_e32 v58, v126
	v_mov_b32_e32 v59, v127
	s_nop 0
	v_mov_b32_e32 v60, v108
	v_mov_b32_e32 v61, v109
	v_mov_b32_e32 v62, v110
	v_mov_b32_e32 v63, v111
	v_pk_add_f32 v[58:59], v[58:59], 1.0 op_sel_hi:[1,0]
	v_pk_add_f32 v[56:57], v[56:57], 1.0 op_sel_hi:[1,0]
	v_pk_mul_f32 v[58:59], v[62:63], v[58:59]
	v_pk_mul_f32 v[56:57], v[60:61], v[56:57]
	v_pk_mul_f32 v[54:55], v[54:55], v[58:59]
	v_pk_mul_f32 v[52:53], v[52:53], v[56:57]
	s_nop 0
	v_cvt_pk_bf16_f32 v52, v52, v53
	v_cvt_pk_bf16_f32 v53, v54, v55
	global_store_dwordx2 v[88:89], v[52:53], off offset:1024
	v_mov_b32_e32 v52, v128
	v_mov_b32_e32 v53, v129
	v_mov_b32_e32 v54, v130
	v_mov_b32_e32 v55, v131
	s_nop 0
	v_mov_b32_e32 v56, v112
	v_mov_b32_e32 v57, v113
	v_mov_b32_e32 v58, v114
	v_mov_b32_e32 v59, v115
	v_pk_add_f32 v[54:55], v[54:55], 1.0 op_sel_hi:[1,0]
	v_pk_add_f32 v[52:53], v[52:53], 1.0 op_sel_hi:[1,0]
	v_pk_mul_f32 v[54:55], v[58:59], v[54:55]
	v_pk_mul_f32 v[52:53], v[56:57], v[52:53]
	v_pk_mul_f32 v[50:51], v[50:51], v[54:55]
	v_pk_mul_f32 v[48:49], v[48:49], v[52:53]
	s_nop 0
	v_cvt_pk_bf16_f32 v48, v48, v49
	v_cvt_pk_bf16_f32 v49, v50, v51
	global_store_dwordx2 v[88:89], v[48:49], off offset:1536
	s_cbranch_vccnz .LBB0_110
	v_mul_f32_e32 v48, v45, v45
	v_mul_f32_e32 v49, v47, v47
	v_fmac_f32_e32 v48, v44, v44
	v_fmac_f32_e32 v49, v46, v46
	v_add_f32_e32 v48, v48, v49
	v_mul_f32_e32 v49, v41, v41
	v_mul_f32_e32 v50, v43, v43
	v_fmac_f32_e32 v49, v40, v40
	v_fmac_f32_e32 v50, v42, v42
	v_add_f32_e32 v49, v49, v50
	v_add_f32_e32 v48, v48, v49
	v_mul_f32_e32 v49, v37, v37
	v_mul_f32_e32 v50, v39, v39
	v_fmac_f32_e32 v49, v36, v36
	v_fmac_f32_e32 v50, v38, v38
	v_add_f32_e32 v49, v49, v50
	v_add_f32_e32 v48, v48, v49
	v_mul_f32_e32 v49, v33, v33
	v_mul_f32_e32 v50, v35, v35
	v_fmac_f32_e32 v49, v32, v32
	v_fmac_f32_e32 v50, v34, v34
	v_add_f32_e32 v49, v49, v50
	v_add_f32_e32 v48, v48, v49
	ds_swizzle_b32 v49, v48 offset:swizzle(SWAP,1)
	s_waitcnt lgkmcnt(0)
	v_add_f32_e32 v48, v48, v49
	ds_swizzle_b32 v49, v48 offset:swizzle(SWAP,2)
	s_waitcnt lgkmcnt(0)
	v_add_f32_e32 v48, v48, v49
	ds_swizzle_b32 v49, v48 offset:swizzle(SWAP,4)
	s_waitcnt lgkmcnt(0)
	v_add_f32_e32 v48, v48, v49
	ds_swizzle_b32 v49, v48 offset:swizzle(SWAP,8)
	s_waitcnt lgkmcnt(0)
	v_add_f32_e32 v48, v48, v49
	ds_swizzle_b32 v49, v48 offset:swizzle(SWAP,16)
	s_waitcnt lgkmcnt(0)
	v_add_f32_e32 v48, v48, v49
	ds_bpermute_b32 v49, v76, v48
	s_and_saveexec_b64 s[46:47], s[4:5]
	s_cbranch_execz .LBB0_116
	s_waitcnt lgkmcnt(0)
	v_add_f32_e32 v48, v48, v49
	v_mul_f32_e32 v48, 0x4f800000, v48
	v_trunc_f32_e32 v48, v48
	v_mul_f32_e32 v49, 0x2f800000, v48
	v_floor_f32_e32 v49, v49
	v_fmac_f32_e32 v48, 0xcf800000, v49
	v_cvt_u32_f32_e32 v48, v48
	v_cvt_u32_f32_e32 v49, v49
	s_add_u32 s48, s30, s14
	s_addc_u32 s49, s31, s15
	global_store_dwordx2 v77, v[48:49], s[48:49]
; DI unsigned cvtpk(float lo, float hi) { f32x2_t v = {lo, hi}; bf16x2_t b = __builtin_convertvector(v, bf16x2_t); return __builtin_bit_cast(unsigned, b); }
; DI void xs0_phase(const float* xs, const float* gain, const float* mod_l, bf16* h, unsigned long long* rowsq, int NGW, const int wave_s) {
;     ...
;         for (int r = 0; r < 4; ++r) { const int m = m0 + r * NGW; if (m >= MTOK) break;
;             const int b = m >> 12; float ss = 0.f;
; #pragma unroll
;             for (int j = 0; j < 4; ++j) ss += (v[r][j].x * v[r][j].x + v[r][j].y * v[r][j].y) + (v[r][j].z * v[r][j].z + v[r][j].w * v[r][j].w);
;             ss = wave_sum(ss, x32);
;             if (lane == 0) rowsq[m] = (unsigned long long)(ss * 4294967296.f);
;             unsigned long long* o8 = (unsigned long long*)(h + (size_t)m * DM) + lane;
; #pragma unroll
;             for (int j = 0; j < 4; ++j) { const int col = 4 * lane + 256 * j;
;                 const f32x4 g = *(const f32x4*)(gain + col), sc = *(const f32x4*)(mod_l + (size_t)b * 6144 + DM + col);
;                 const f32x4 y = v[r][j] * (g * (sc + 1.f));
;                 o8[64 * j] = (unsigned long long)cvtpk(y.x, y.y) | ((unsigned long long)cvtpk(y.z, y.w) << 32); } }
.LBB0_116:
	s_or_b64 exec, exec, s[46:47]
	s_ashr_i32 s35, s35, 12
	s_mul_hi_i32 s39, s35, 0x6000
	s_mulk_i32 s35, 0x6000
	s_add_u32 s46, s8, s35
	s_addc_u32 s47, s9, s39
	v_lshl_add_u64 v[56:57], v[64:65], 2, s[46:47]
	v_add_co_u32_e32 v48, vcc, s7, v56
	v_lshl_add_u64 v[58:59], s[18:19], 0, v[68:69]
	s_waitcnt lgkmcnt(0)
	v_addc_co_u32_e32 v49, vcc, 0, v57, vcc
	v_mov_b32_e32 v48, v132
	v_mov_b32_e32 v49, v133
	v_mov_b32_e32 v50, v134
	v_mov_b32_e32 v51, v135
	s_nop 0
	v_mov_b32_e32 v52, v100
	v_mov_b32_e32 v53, v101
	v_mov_b32_e32 v54, v102
	v_mov_b32_e32 v55, v103
	v_add_co_u32_e32 v58, vcc, s13, v58
	v_lshl_add_u64 v[56:57], v[56:57], 0, s[28:29]
	s_nop 0
	v_addc_co_u32_e32 v59, vcc, 0, v59, vcc
	s_andn2_b64 vcc, exec, s[40:41]
	v_pk_add_f32 v[50:51], v[50:51], 1.0 op_sel_hi:[1,0]
	v_pk_add_f32 v[48:49], v[48:49], 1.0 op_sel_hi:[1,0]
	v_pk_mul_f32 v[50:51], v[54:55], v[50:51]
	v_pk_mul_f32 v[48:49], v[52:53], v[48:49]
	v_pk_mul_f32 v[46:47], v[46:47], v[50:51]
	v_pk_mul_f32 v[44:45], v[44:45], v[48:49]
	s_nop 0
	v_cvt_pk_bf16_f32 v44, v44, v45
	v_cvt_pk_bf16_f32 v45, v46, v47
	global_store_dwordx2 v[58:59], v[44:45], off
	v_mov_b32_e32 v44, v136
	v_mov_b32_e32 v45, v137
	v_mov_b32_e32 v46, v138
	v_mov_b32_e32 v47, v139
	s_nop 0
	v_mov_b32_e32 v48, v104
	v_mov_b32_e32 v49, v105
	v_mov_b32_e32 v50, v106
	v_mov_b32_e32 v51, v107
	v_pk_add_f32 v[46:47], v[46:47], 1.0 op_sel_hi:[1,0]
	v_pk_add_f32 v[44:45], v[44:45], 1.0 op_sel_hi:[1,0]
	v_pk_mul_f32 v[46:47], v[50:51], v[46:47]
	v_pk_mul_f32 v[44:45], v[48:49], v[44:45]
	v_pk_mul_f32 v[42:43], v[42:43], v[46:47]
	v_pk_mul_f32 v[40:41], v[40:41], v[44:45]
	s_nop 0
	v_cvt_pk_bf16_f32 v40, v40, v41
	v_cvt_pk_bf16_f32 v41, v42, v43
	global_store_dwordx2 v[58:59], v[40:41], off offset:512
	v_mov_b32_e32 v40, v140
	v_mov_b32_e32 v41, v141
	v_mov_b32_e32 v42, v142
	v_mov_b32_e32 v43, v143
	s_nop 0
	v_mov_b32_e32 v44, v108
	v_mov_b32_e32 v45, v109
	v_mov_b32_e32 v46, v110
	v_mov_b32_e32 v47, v111
	v_pk_add_f32 v[42:43], v[42:43], 1.0 op_sel_hi:[1,0]
	v_pk_add_f32 v[40:41], v[40:41], 1.0 op_sel_hi:[1,0]
	v_pk_mul_f32 v[42:43], v[46:47], v[42:43]
	v_pk_mul_f32 v[40:41], v[44:45], v[40:41]
	v_pk_mul_f32 v[38:39], v[38:39], v[42:43]
	v_pk_mul_f32 v[36:37], v[36:37], v[40:41]
	s_nop 0
	v_cvt_pk_bf16_f32 v36, v36, v37
	v_cvt_pk_bf16_f32 v37, v38, v39
	global_store_dwordx2 v[58:59], v[36:37], off offset:1024
	v_mov_b32_e32 v36, v144
	v_mov_b32_e32 v37, v145
	v_mov_b32_e32 v38, v146
	v_mov_b32_e32 v39, v147
	s_nop 0
	v_mov_b32_e32 v40, v112
	v_mov_b32_e32 v41, v113
	v_mov_b32_e32 v42, v114
	v_mov_b32_e32 v43, v115
	v_pk_add_f32 v[38:39], v[38:39], 1.0 op_sel_hi:[1,0]
	v_pk_add_f32 v[36:37], v[36:37], 1.0 op_sel_hi:[1,0]
	v_pk_mul_f32 v[38:39], v[42:43], v[38:39]
	v_pk_mul_f32 v[36:37], v[40:41], v[36:37]
	v_pk_mul_f32 v[34:35], v[34:35], v[38:39]
	v_pk_mul_f32 v[32:33], v[32:33], v[36:37]
	s_nop 0
	v_cvt_pk_bf16_f32 v32, v32, v33
	v_cvt_pk_bf16_f32 v33, v34, v35
	global_store_dwordx2 v[58:59], v[32:33], off offset:1536
	s_cbranch_vccnz .LBB0_110
	v_mul_f32_e32 v32, v29, v29
	v_mul_f32_e32 v33, v31, v31
	v_fmac_f32_e32 v32, v28, v28
	v_fmac_f32_e32 v33, v30, v30
	v_add_f32_e32 v32, v32, v33
	v_mul_f32_e32 v33, v25, v25
	v_mul_f32_e32 v34, v27, v27
	v_fmac_f32_e32 v33, v24, v24
	v_fmac_f32_e32 v34, v26, v26
	v_add_f32_e32 v33, v33, v34
	v_add_f32_e32 v32, v32, v33
	v_mul_f32_e32 v33, v21, v21
	v_mul_f32_e32 v34, v23, v23
	v_fmac_f32_e32 v33, v20, v20
	v_fmac_f32_e32 v34, v22, v22
	v_add_f32_e32 v33, v33, v34
	v_add_f32_e32 v32, v32, v33
	v_mul_f32_e32 v33, v17, v17
	v_mul_f32_e32 v34, v19, v19
	v_fmac_f32_e32 v33, v16, v16
	v_fmac_f32_e32 v34, v18, v18
	v_add_f32_e32 v33, v33, v34
	v_add_f32_e32 v32, v32, v33
	ds_swizzle_b32 v33, v32 offset:swizzle(SWAP,1)
	s_ashr_i32 s39, s38, 31
	s_waitcnt lgkmcnt(0)
	v_add_f32_e32 v32, v32, v33
	ds_swizzle_b32 v33, v32 offset:swizzle(SWAP,2)
	s_waitcnt lgkmcnt(0)
	v_add_f32_e32 v32, v32, v33
	ds_swizzle_b32 v33, v32 offset:swizzle(SWAP,4)
	s_waitcnt lgkmcnt(0)
	v_add_f32_e32 v32, v32, v33
	ds_swizzle_b32 v33, v32 offset:swizzle(SWAP,8)
	s_waitcnt lgkmcnt(0)
	v_add_f32_e32 v32, v32, v33
	ds_swizzle_b32 v33, v32 offset:swizzle(SWAP,16)
	s_waitcnt lgkmcnt(0)
	v_add_f32_e32 v32, v32, v33
	ds_bpermute_b32 v33, v76, v32
	s_and_saveexec_b64 s[40:41], s[4:5]
	s_cbranch_execz .LBB0_119
	s_waitcnt lgkmcnt(0)
	v_add_f32_e32 v32, v32, v33
	v_mul_f32_e32 v32, 0x4f800000, v32
	v_trunc_f32_e32 v32, v32
	v_mul_f32_e32 v33, 0x2f800000, v32
	v_floor_f32_e32 v33, v33
	v_fmac_f32_e32 v32, 0xcf800000, v33
	v_cvt_u32_f32_e32 v32, v32
	v_cvt_u32_f32_e32 v33, v33
	s_lshl_b64 s[46:47], s[38:39], 3
	s_add_u32 s46, s10, s46
	s_addc_u32 s47, s11, s47
	global_store_dwordx2 v77, v[32:33], s[46:47]
; DI unsigned cvtpk(float lo, float hi) { f32x2_t v = {lo, hi}; bf16x2_t b = __builtin_convertvector(v, bf16x2_t); return __builtin_bit_cast(unsigned, b); }
; DI void xs0_phase(const float* xs, const float* gain, const float* mod_l, bf16* h, unsigned long long* rowsq, int NGW, const int wave_s) {
;     ...
;         for (int r = 0; r < 4; ++r) { const int m = m0 + r * NGW; if (m >= MTOK) break;
;             const int b = m >> 12; float ss = 0.f;
; #pragma unroll
;             for (int j = 0; j < 4; ++j) ss += (v[r][j].x * v[r][j].x + v[r][j].y * v[r][j].y) + (v[r][j].z * v[r][j].z + v[r][j].w * v[r][j].w);
;             ss = wave_sum(ss, x32);
;             if (lane == 0) rowsq[m] = (unsigned long long)(ss * 4294967296.f);
;             unsigned long long* o8 = (unsigned long long*)(h + (size_t)m * DM) + lane;
; #pragma unroll
;             for (int j = 0; j < 4; ++j) { const int col = 4 * lane + 256 * j;
;                 const f32x4 g = *(const f32x4*)(gain + col), sc = *(const f32x4*)(mod_l + (size_t)b * 6144 + DM + col);
;                 const f32x4 y = v[r][j] * (g * (sc + 1.f));
;                 o8[64 * j] = (unsigned long long)cvtpk(y.x, y.y) | ((unsigned long long)cvtpk(y.z, y.w) << 32); } }
.LBB0_119:
	s_or_b64 exec, exec, s[40:41]
	s_ashr_i32 s35, s38, 12
	s_lshl_b64 s[38:39], s[38:39], 11
	s_mul_hi_i32 s41, s35, 0x6000
	s_mulk_i32 s35, 0x6000
	s_add_u32 s40, s8, s35
	s_addc_u32 s41, s9, s41
	v_lshl_add_u64 v[40:41], v[64:65], 2, s[40:41]
	v_add_co_u32_e32 v32, vcc, s7, v40
	v_lshl_add_u64 v[42:43], v[70:71], 0, s[38:39]
	s_waitcnt lgkmcnt(0)
	v_addc_co_u32_e32 v33, vcc, 0, v41, vcc
	v_mov_b32_e32 v32, v148
	v_mov_b32_e32 v33, v149
	v_mov_b32_e32 v34, v150
	v_mov_b32_e32 v35, v151
	s_nop 0
	v_mov_b32_e32 v36, v100
	v_mov_b32_e32 v37, v101
	v_mov_b32_e32 v38, v102
	v_mov_b32_e32 v39, v103
	v_lshl_add_u64 v[40:41], v[40:41], 0, s[28:29]
	s_andn2_b64 vcc, exec, s[36:37]
	v_pk_add_f32 v[34:35], v[34:35], 1.0 op_sel_hi:[1,0]
	v_pk_add_f32 v[32:33], v[32:33], 1.0 op_sel_hi:[1,0]
	v_pk_mul_f32 v[34:35], v[38:39], v[34:35]
	v_pk_mul_f32 v[32:33], v[36:37], v[32:33]
	v_pk_mul_f32 v[30:31], v[30:31], v[34:35]
	v_pk_mul_f32 v[28:29], v[28:29], v[32:33]
	s_nop 0
	v_cvt_pk_bf16_f32 v28, v28, v29
	v_cvt_pk_bf16_f32 v29, v30, v31
	global_store_dwordx2 v[42:43], v[28:29], off
	v_mov_b32_e32 v28, v152
	v_mov_b32_e32 v29, v153
	v_mov_b32_e32 v30, v154
	v_mov_b32_e32 v31, v155
	s_nop 0
	v_mov_b32_e32 v32, v104
	v_mov_b32_e32 v33, v105
	v_mov_b32_e32 v34, v106
	v_mov_b32_e32 v35, v107
	v_pk_add_f32 v[30:31], v[30:31], 1.0 op_sel_hi:[1,0]
	v_pk_add_f32 v[28:29], v[28:29], 1.0 op_sel_hi:[1,0]
	v_pk_mul_f32 v[30:31], v[34:35], v[30:31]
	v_pk_mul_f32 v[28:29], v[32:33], v[28:29]
	v_pk_mul_f32 v[26:27], v[26:27], v[30:31]
	v_pk_mul_f32 v[24:25], v[24:25], v[28:29]
	s_nop 0
	v_cvt_pk_bf16_f32 v24, v24, v25
	v_cvt_pk_bf16_f32 v25, v26, v27
	global_store_dwordx2 v[42:43], v[24:25], off offset:512
	v_mov_b32_e32 v24, v156
	v_mov_b32_e32 v25, v157
	v_mov_b32_e32 v26, v158
	v_mov_b32_e32 v27, v159
	s_nop 0
	v_mov_b32_e32 v28, v108
	v_mov_b32_e32 v29, v109
	v_mov_b32_e32 v30, v110
	v_mov_b32_e32 v31, v111
	v_pk_add_f32 v[26:27], v[26:27], 1.0 op_sel_hi:[1,0]
	v_pk_add_f32 v[24:25], v[24:25], 1.0 op_sel_hi:[1,0]
	v_pk_mul_f32 v[26:27], v[30:31], v[26:27]
	v_pk_mul_f32 v[24:25], v[28:29], v[24:25]
	v_pk_mul_f32 v[22:23], v[22:23], v[26:27]
	v_pk_mul_f32 v[20:21], v[20:21], v[24:25]
	s_nop 0
	v_cvt_pk_bf16_f32 v20, v20, v21
	v_cvt_pk_bf16_f32 v21, v22, v23
	global_store_dwordx2 v[42:43], v[20:21], off offset:1024
	v_mov_b32_e32 v20, v160
	v_mov_b32_e32 v21, v161
	v_mov_b32_e32 v22, v162
	v_mov_b32_e32 v23, v163
	s_nop 0
	v_mov_b32_e32 v24, v112
	v_mov_b32_e32 v25, v113
	v_mov_b32_e32 v26, v114
	v_mov_b32_e32 v27, v115
	v_pk_add_f32 v[22:23], v[22:23], 1.0 op_sel_hi:[1,0]
	v_pk_add_f32 v[20:21], v[20:21], 1.0 op_sel_hi:[1,0]
	v_pk_mul_f32 v[22:23], v[26:27], v[22:23]
	v_pk_mul_f32 v[20:21], v[24:25], v[20:21]
	v_pk_mul_f32 v[18:19], v[18:19], v[22:23]
	v_pk_mul_f32 v[16:17], v[16:17], v[20:21]
	s_nop 0
	v_cvt_pk_bf16_f32 v16, v16, v17
	v_cvt_pk_bf16_f32 v17, v18, v19
	global_store_dwordx2 v[42:43], v[16:17], off offset:1536
	s_cbranch_vccnz .LBB0_110
	v_mul_f32_e32 v16, v13, v13
	v_mul_f32_e32 v17, v15, v15
	v_fmac_f32_e32 v16, v12, v12
	v_fmac_f32_e32 v17, v14, v14
	v_add_f32_e32 v16, v16, v17
	v_mul_f32_e32 v17, v9, v9
	v_mul_f32_e32 v18, v11, v11
	v_fmac_f32_e32 v17, v8, v8
	v_fmac_f32_e32 v18, v10, v10
	v_add_f32_e32 v17, v17, v18
	v_add_f32_e32 v16, v16, v17
	v_mul_f32_e32 v17, v5, v5
	v_mul_f32_e32 v18, v7, v7
	v_fmac_f32_e32 v17, v4, v4
	v_fmac_f32_e32 v18, v6, v6
	v_add_f32_e32 v17, v17, v18
	v_add_f32_e32 v16, v16, v17
	v_mul_f32_e32 v17, v1, v1
	v_mul_f32_e32 v18, v3, v3
	v_fmac_f32_e32 v17, v0, v0
	v_fmac_f32_e32 v18, v2, v2
	v_add_f32_e32 v17, v17, v18
	v_add_f32_e32 v16, v16, v17
	ds_swizzle_b32 v17, v16 offset:swizzle(SWAP,1)
	s_ashr_i32 s35, s34, 31
	s_waitcnt lgkmcnt(0)
	v_add_f32_e32 v16, v16, v17
	ds_swizzle_b32 v17, v16 offset:swizzle(SWAP,2)
	s_waitcnt lgkmcnt(0)
	v_add_f32_e32 v16, v16, v17
	ds_swizzle_b32 v17, v16 offset:swizzle(SWAP,4)
	s_waitcnt lgkmcnt(0)
	v_add_f32_e32 v16, v16, v17
	ds_swizzle_b32 v17, v16 offset:swizzle(SWAP,8)
	s_waitcnt lgkmcnt(0)
	v_add_f32_e32 v16, v16, v17
	ds_swizzle_b32 v17, v16 offset:swizzle(SWAP,16)
	s_waitcnt lgkmcnt(0)
	v_add_f32_e32 v16, v16, v17
	ds_bpermute_b32 v17, v76, v16
	s_and_saveexec_b64 s[36:37], s[4:5]
	s_cbranch_execz .LBB0_109
	s_waitcnt lgkmcnt(0)
	v_add_f32_e32 v16, v16, v17
	v_mul_f32_e32 v16, 0x4f800000, v16
	v_trunc_f32_e32 v16, v16
	v_mul_f32_e32 v17, 0x2f800000, v16
	v_floor_f32_e32 v17, v17
	v_fmac_f32_e32 v16, 0xcf800000, v17
	v_cvt_u32_f32_e32 v16, v16
	v_cvt_u32_f32_e32 v17, v17
	s_lshl_b64 s[38:39], s[34:35], 3
	s_add_u32 s38, s10, s38
	s_addc_u32 s39, s11, s39
	global_store_dwordx2 v77, v[16:17], s[38:39]
	s_branch .LBB0_109

; #define LAS __attribute__((address_space(3)))
; __global__ void __launch_bounds__(NTHREADS, 2) trunk_fwd(Params p) {
;     extern __shared__ __attribute__((aligned(16))) unsigned char lds_raw[];
;     cg::grid_group grid = cg::this_grid();
;     LAS unsigned char* lds = (LAS unsigned char*)lds_raw;
;     const int tid = threadIdx.x, lane = tid & 63, wave = __builtin_amdgcn_readfirstlane(tid >> 6); const int wave_s = wave;
;     const int G = gridDim.x, gw = blockIdx.x * NWAVES + wave, NGW = G * NWAVES;
	.amdhsa_kernel _Z9trunk_fwd6Params
		.amdhsa_group_segment_fixed_size 0
		.amdhsa_private_segment_fixed_size 0
		.amdhsa_kernarg_size 408
		.amdhsa_user_sgpr_count 2
		.amdhsa_user_sgpr_dispatch_ptr 0
		.amdhsa_user_sgpr_queue_ptr 0
		.amdhsa_user_sgpr_kernarg_segment_ptr 1
		.amdhsa_user_sgpr_dispatch_id 0
		.amdhsa_user_sgpr_kernarg_preload_length 0
		.amdhsa_user_sgpr_kernarg_preload_offset 0
		.amdhsa_user_sgpr_private_segment_size 0
		.amdhsa_uses_dynamic_stack 0
		.amdhsa_enable_private_segment 0
		.amdhsa_system_sgpr_workgroup_id_x 1
		.amdhsa_system_sgpr_workgroup_id_y 0
		.amdhsa_system_sgpr_workgroup_id_z 0
		.amdhsa_system_sgpr_workgroup_info 0
		.amdhsa_system_vgpr_workitem_id 2
		.amdhsa_next_free_vgpr 256
		.amdhsa_next_free_sgpr 102
		.amdhsa_accum_offset 256
		.amdhsa_reserve_vcc 1
		.amdhsa_float_round_mode_32 0
		.amdhsa_float_round_mode_16_64 0
		.amdhsa_float_denorm_mode_32 3
		.amdhsa_float_denorm_mode_16_64 3
		.amdhsa_dx10_clamp 1
		.amdhsa_ieee_mode 1
		.amdhsa_fp16_overflow 0
		.amdhsa_tg_split 0
		.amdhsa_exception_fp_ieee_invalid_op 0
		.amdhsa_exception_fp_denorm_src 0
		.amdhsa_exception_fp_ieee_div_zero 0
		.amdhsa_exception_fp_ieee_overflow 0
		.amdhsa_exception_fp_ieee_underflow 0
		.amdhsa_exception_fp_ieee_inexact 0
		.amdhsa_exception_int_div_zero 0
	.end_amdhsa_kernel

; #define LAS __attribute__((address_space(3)))
; __global__ void __launch_bounds__(NTHREADS, 2) trunk_fwd(Params p) {
;     extern __shared__ __attribute__((aligned(16))) unsigned char lds_raw[];
;     cg::grid_group grid = cg::this_grid();
;     LAS unsigned char* lds = (LAS unsigned char*)lds_raw;
;     const int tid = threadIdx.x, lane = tid & 63, wave = __builtin_amdgcn_readfirstlane(tid >> 6); const int wave_s = wave;
;     const int G = gridDim.x, gw = blockIdx.x * NWAVES + wave, NGW = G * NWAVES;
amdhsa.kernels:
  - .agpr_count:     0
    .args:
      - .offset:         0
        .size:           152
        .value_kind:     by_value
      - .offset:         152
        .size:           4
        .value_kind:     hidden_block_count_x
      - .offset:         156
        .size:           4
        .value_kind:     hidden_block_count_y
      - .offset:         160
        .size:           4
        .value_kind:     hidden_block_count_z
      - .offset:         164
        .size:           2
        .value_kind:     hidden_group_size_x
      - .offset:         166
        .size:           2
        .value_kind:     hidden_group_size_y
      - .offset:         168
        .size:           2
        .value_kind:     hidden_group_size_z
      - .offset:         170
        .size:           2
        .value_kind:     hidden_remainder_x
      - .offset:         172
        .size:           2
        .value_kind:     hidden_remainder_y
      - .offset:         174
        .size:           2
        .value_kind:     hidden_remainder_z
      - .offset:         192
        .size:           8
        .value_kind:     hidden_global_offset_x
      - .offset:         200
        .size:           8
        .value_kind:     hidden_global_offset_y
      - .offset:         208
        .size:           8
        .value_kind:     hidden_global_offset_z
      - .offset:         216
        .size:           2
        .value_kind:     hidden_grid_dims
      - .offset:         240
        .size:           8
        .value_kind:     hidden_multigrid_sync_arg
      - .offset:         272
        .size:           4
        .value_kind:     hidden_dynamic_lds_size
    .group_segment_fixed_size: 0
    .kernarg_segment_align: 8
    .kernarg_segment_size: 408
    .language:       OpenCL C
    .language_version:
      - 2
      - 0
    .max_flat_workgroup_size: 512
    .name:           _Z9trunk_fwd6Params
    .private_segment_fixed_size: 0
    .sgpr_count:     108
    .sgpr_spill_count: 63
    .symbol:         _Z9trunk_fwd6Params.kd
    .uniform_work_group_size: 1
    .uses_dynamic_stack: false
    .vgpr_count:     256
    .vgpr_spill_count: 0
    .wavefront_size: 64
